# sc1 (L1 bypass) on indexer K loads and attention gathers
# baseline (speedup 1.0000x reference)
; #define TILE_LOAD(SLOT, CC, TT) do { const bf16_t* kp = P.KI + (rowb + 64 * (CC) + 16 * (TT) + r16) * 64 + 8 * g; Bk[SLOT][0] = *(const bf16x8*)kp; Bk[SLOT][1] = *(const bf16x8*)(kp + 32); } while (0)
; #define TILE_MATH(SLOT, TT) do { _Pragma("unroll") for (int q = 0; q < 4; ++q) { f32x4 a = {0.f, 0.f, 0.f, 0.f}; \
;             a = mfma16(Aq[q][0], Bk[SLOT][0], a); a = mfma16(Aq[q][1], Bk[SLOT][1], a); \
;             pv[q][TT] = wq[q][0] * fmaxf(a[0], 0.f) + wq[q][1] * fmaxf(a[1], 0.f) + wq[q][2] * fmaxf(a[2], 0.f) + wq[q][3] * fmaxf(a[3], 0.f); } } while (0)
; __device__ __forceinline__ void attn_item(const Ptrs& P, unsigned char* lds, int b, int tq0, int tid) {
;     ...
;     if (tmax < 256 || (DBG & 4)) {
;         for (int i = tid; i < 1024; i += 512) sel[i] = (unsigned short)(((i & 255) <= tq0 + (i >> 8)) ? (i & 255) : 0);
;         __syncthreads();
;     } else {
;         bf16x8 Aq[4][2]; f32x4 wq[4];
; #pragma unroll
;         for (int q = 0; q < 4; ++q) { const bf16_t* qp = P.QI + (rowb + tq0 + q) * 1024 + r16 * 64 + 8 * g; Aq[q][0] = *(const bf16x8*)qp; Aq[q][1] = *(const bf16x8*)(qp + 32);
;             wq[q] = *(const f32x4*)(P.WI + (rowb + tq0 + q) * 16 + 4 * g); }
;         unsigned* KB = (unsigned*)lds;
;         const int nch = (tmax >> 6) + 1;
;         const int ni = (w < nch) ? ((nch - w + 7) >> 3) : 0;
;         bf16x8 Bk[4][2];
;     ...
;         if (ni > 0) { TILE_LOAD(0, w, 0); TILE_LOAD(1, w, 1); }
; #pragma unroll 1
;         for (int it = 0; it < ni; ++it) {
;             const int c = 8 * it + w; const bool more = it + 1 < ni;
;             float pv[4][4], sv[4];
;             TILE_LOAD(2, c, 2); TILE_MATH(0, 0);
;             TILE_LOAD(3, c, 3); TILE_MATH(1, 1);
;             if (more) TILE_LOAD(0, c + 8, 0);
;             TILE_MATH(2, 2);
;             if (more) TILE_LOAD(1, c + 8, 1);
;             TILE_MATH(3, 3);
.Lq_have_item:
	s_movk_i32 s12, 0x800
	s_waitcnt lgkmcnt(0)
	v_cmp_gt_i32_e32 vcc, s12, v0
	s_mov_b64 s[12:13], -1
	s_and_saveexec_b64 s[70:71], vcc
	s_cbranch_execz .LBB0_465
	v_lshlrev_b32_e32 v64, 2, v0
	v_sub_u32_e32 v124, 0x1ffc, v64
	v_readfirstlane_b32 s63, v188
	s_movk_i32 s12, 0xfc
	s_lshr_b32 s62, s63, 6
	v_cmp_lt_u32_e32 vcc, s12, v124
	s_and_saveexec_b64 s[12:13], vcc
	s_xor_b64 s[60:61], exec, s[12:13]
	s_cbranch_execz .LBB0_913
	v_sub_u32_e32 v126, 0x1fff, v64
	v_lshrrev_b32_e32 v125, 6, v126
	v_subrev_u32_e32 v0, s62, v125
	v_add_u32_e32 v65, 8, v0
	v_cmp_le_u32_e32 vcc, s62, v125
	v_cmp_lt_u32_e64 s[12:13], 7, v65
	s_and_b64 s[14:15], vcc, s[12:13]
	s_and_saveexec_b64 s[12:13], s[14:15]
	s_cbranch_execz .LBB0_479
	s_and_b32 s14, s63, 0xffffffc0
	v_add_u32_e32 v164, s81, v124
	s_ashr_i32 s15, s14, 31
	v_or_b32_e32 v40, 1, v164
	v_mov_b32_e32 v41, v165
	v_or_b32_e32 v32, 2, v164
	v_mov_b32_e32 v33, v165
	v_or_b32_e32 v34, 3, v164
	v_mov_b32_e32 v35, v165
	v_lshl_add_u64 v[48:49], s[14:15], 0, v[182:183]
	v_lshlrev_b64 v[0:1], 11, v[164:165]
	v_lshlrev_b64 v[8:9], 11, v[40:41]
	v_lshlrev_b64 v[16:17], 11, v[32:33]
	v_lshlrev_b64 v[24:25], 11, v[34:35]
	v_lshlrev_b64 v[34:35], 6, v[34:35]
	v_lshlrev_b64 v[32:33], 6, v[32:33]
	v_lshlrev_b64 v[40:41], 6, v[40:41]
	v_lshlrev_b64 v[42:43], 6, v[164:165]
	v_lshlrev_b64 v[48:49], 7, v[48:49]
	v_lshl_add_u64 v[4:5], v[168:169], 0, v[0:1]
	v_lshl_add_u64 v[12:13], v[168:169], 0, v[8:9]
	v_lshl_add_u64 v[20:21], v[168:169], 0, v[16:17]
	v_lshl_add_u64 v[28:29], v[168:169], 0, v[24:25]
	v_lshl_add_u64 v[34:35], v[170:171], 0, v[34:35]
	v_lshl_add_u64 v[36:37], v[170:171], 0, v[32:33]
	v_lshl_add_u64 v[40:41], v[170:171], 0, v[40:41]
	v_lshl_add_u64 v[44:45], v[170:171], 0, v[42:43]
	v_lshl_add_u64 v[60:61], v[172:173], 0, v[48:49]
	global_load_dwordx4 v[0:3], v[4:5], off
	s_nop 0
	global_load_dwordx4 v[4:7], v[4:5], off offset:64
	s_nop 0
	global_load_dwordx4 v[8:11], v[12:13], off
	s_nop 0
	global_load_dwordx4 v[12:15], v[12:13], off offset:64
	s_nop 0
	global_load_dwordx4 v[16:19], v[20:21], off
	s_nop 0
	global_load_dwordx4 v[20:23], v[20:21], off offset:64
	s_nop 0
	global_load_dwordx4 v[24:27], v[28:29], off
	s_nop 0
	global_load_dwordx4 v[28:31], v[28:29], off offset:64
	s_nop 0
	global_load_dwordx4 v[32:35], v[34:35], off
	s_nop 0
	global_load_dwordx4 v[36:39], v[36:37], off
	s_nop 0
	global_load_dwordx4 v[40:43], v[40:41], off
	s_nop 0
	global_load_dwordx4 v[44:47], v[44:45], off
	s_nop 0
	v_lshrrev_b32_e32 v127, 3, v65
	v_sub_u32_e32 v128, 0x1ffd, v64
	v_sub_u32_e32 v129, 0x1ffe, v64
	v_mov_b64_e32 v[150:151], v[60:61]
	s_mov_b64 s[18:19], 0x1000
	v_lshl_add_u64 v[152:153], v[60:61], 0, s[18:19]
	global_load_dwordx4 v[48:51], v[150:151], off sc1
	global_load_dwordx4 v[52:55], v[150:151], off offset:1024 sc1
	global_load_dwordx4 v[56:59], v[150:151], off offset:2048 sc1
	global_load_dwordx4 v[60:63], v[150:151], off offset:3072 sc1
	global_load_dwordx4 v[64:67], v[152:153], off sc1
	global_load_dwordx4 v[68:71], v[152:153], off offset:1024 sc1
	global_load_dwordx4 v[72:75], v[152:153], off offset:2048 sc1
	global_load_dwordx4 v[76:79], v[152:153], off offset:3072 sc1
	s_mov_b64 s[18:19], 0x10000
	v_lshl_add_u64 v[150:151], v[150:151], 0, s[18:19]
	v_lshl_add_u64 v[152:153], v[152:153], 0, s[18:19]
	s_mov_b32 s20, 0
	v_lshl_add_u32 v130, s62, 8, v203
	v_add_u32_e32 v155, 0x10000, v130
	v_add_u32_e32 v154, s14, v179
	s_nop 0
	v_readfirstlane_b32 s14, v127
.Lidx_loop:
	s_waitcnt vmcnt(6)
	v_mfma_f32_16x16x32_bf16 v[80:83], v[0:3], v[48:51], 0
	v_mfma_f32_16x16x32_bf16 v[84:87], v[8:11], v[48:51], 0
	v_mfma_f32_16x16x32_bf16 v[88:91], v[16:19], v[48:51], 0
	v_mfma_f32_16x16x32_bf16 v[92:95], v[24:27], v[48:51], 0
	v_mfma_f32_16x16x32_bf16 v[80:83], v[4:7], v[52:55], v[80:83]
	v_mfma_f32_16x16x32_bf16 v[84:87], v[12:15], v[52:55], v[84:87]
	v_mfma_f32_16x16x32_bf16 v[88:91], v[20:23], v[52:55], v[88:91]
	v_mfma_f32_16x16x32_bf16 v[92:95], v[28:31], v[52:55], v[92:95]
	global_load_dwordx4 v[48:51], v[150:151], off sc1
	global_load_dwordx4 v[52:55], v[150:151], off offset:1024 sc1
	s_waitcnt vmcnt(6)
	v_mfma_f32_16x16x32_bf16 v[96:99], v[0:3], v[56:59], 0
	v_mfma_f32_16x16x32_bf16 v[100:103], v[8:11], v[56:59], 0
	v_mfma_f32_16x16x32_bf16 v[104:107], v[16:19], v[56:59], 0
	v_mfma_f32_16x16x32_bf16 v[108:111], v[24:27], v[56:59], 0
	v_mfma_f32_16x16x32_bf16 v[96:99], v[4:7], v[60:63], v[96:99]
	v_mfma_f32_16x16x32_bf16 v[100:103], v[12:15], v[60:63], v[100:103]
	v_mfma_f32_16x16x32_bf16 v[104:107], v[20:23], v[60:63], v[104:107]
	v_mfma_f32_16x16x32_bf16 v[108:111], v[28:31], v[60:63], v[108:111]
	global_load_dwordx4 v[56:59], v[150:151], off offset:2048 sc1
	global_load_dwordx4 v[60:63], v[150:151], off offset:3072 sc1
	v_max_f32_e32 v80, 0, v80
	v_max_f32_e32 v84, 0, v84
	v_max_f32_e32 v88, 0, v88
	v_max_f32_e32 v92, 0, v92
	v_max_f32_e32 v81, 0, v81
	v_max_f32_e32 v85, 0, v85
	v_max_f32_e32 v89, 0, v89
	v_max_f32_e32 v93, 0, v93
	v_max_f32_e32 v82, 0, v82
	v_max_f32_e32 v86, 0, v86
	v_max_f32_e32 v90, 0, v90
	v_max_f32_e32 v94, 0, v94
	v_max_f32_e32 v83, 0, v83
	v_max_f32_e32 v87, 0, v87
	v_max_f32_e32 v91, 0, v91
	v_max_f32_e32 v95, 0, v95
	v_mul_f32_e32 v132, v44, v80
	v_mul_f32_e32 v136, v40, v84
	v_mul_f32_e32 v140, v36, v88
	v_mul_f32_e32 v144, v32, v92
	v_fmac_f32_e32 v132, v45, v81
	v_fmac_f32_e32 v136, v41, v85
	v_fmac_f32_e32 v140, v37, v89
	v_fmac_f32_e32 v144, v33, v93
	v_fmac_f32_e32 v132, v46, v82
	v_fmac_f32_e32 v136, v42, v86
	v_fmac_f32_e32 v140, v38, v90
	v_fmac_f32_e32 v144, v34, v94
	v_fmac_f32_e32 v132, v47, v83
	v_fmac_f32_e32 v136, v43, v87
	v_fmac_f32_e32 v140, v39, v91
	v_fmac_f32_e32 v144, v35, v95
	s_waitcnt vmcnt(6)
; __device__ __forceinline__ unsigned f2key(float f) { const unsigned u = __builtin_bit_cast(unsigned, f); return (u & 0x80000000u) ? ~u : (u | 0x80000000u); }
; #define TILE_LOAD(SLOT, CC, TT) do { const bf16_t* kp = P.KI + (rowb + 64 * (CC) + 16 * (TT) + r16) * 64 + 8 * g; Bk[SLOT][0] = *(const bf16x8*)kp; Bk[SLOT][1] = *(const bf16x8*)(kp + 32); } while (0)
; #define TILE_MATH(SLOT, TT) do { _Pragma("unroll") for (int q = 0; q < 4; ++q) { f32x4 a = {0.f, 0.f, 0.f, 0.f}; \
;             a = mfma16(Aq[q][0], Bk[SLOT][0], a); a = mfma16(Aq[q][1], Bk[SLOT][1], a); \
;             pv[q][TT] = wq[q][0] * fmaxf(a[0], 0.f) + wq[q][1] * fmaxf(a[1], 0.f) + wq[q][2] * fmaxf(a[2], 0.f) + wq[q][3] * fmaxf(a[3], 0.f); } } while (0)
; __device__ __forceinline__ void attn_item(const Ptrs& P, unsigned char* lds, int b, int tq0, int tid) {
;     ...
;             TILE_LOAD(2, c, 2); TILE_MATH(0, 0);
;             TILE_LOAD(3, c, 3); TILE_MATH(1, 1);
;             if (more) TILE_LOAD(0, c + 8, 0);
;             TILE_MATH(2, 2);
;             if (more) TILE_LOAD(1, c + 8, 1);
;             TILE_MATH(3, 3);
; #pragma unroll
;             for (int q = 0; q < 4; ++q) { float a0 = pv[q][0], b0 = pv[q][2], a1 = pv[q][1], b1 = pv[q][3];
;                 asm("s_nop 1\n\tv_permlane32_swap_b32 %0, %1" : "+v"(a0), "+v"(b0));
;                 asm("s_nop 1\n\tv_permlane32_swap_b32 %0, %1" : "+v"(a1), "+v"(b1));
;                 float x = a0 + b0, y = a1 + b1;
;                 asm("s_nop 1\n\tv_permlane16_swap_b32 %0, %1" : "+v"(x), "+v"(y));
;                 sv[q] = x + y; }
;             const int s = 64 * c + lane;
; #pragma unroll
;             for (int q = 0; q < 4; ++q) KB[q * 8192 + s] = (s <= tq0 + q) ? f2key(sv[q]) : 0u;
	v_mfma_f32_16x16x32_bf16 v[80:83], v[0:3], v[64:67], 0
	v_mfma_f32_16x16x32_bf16 v[84:87], v[8:11], v[64:67], 0
	v_mfma_f32_16x16x32_bf16 v[88:91], v[16:19], v[64:67], 0
	v_mfma_f32_16x16x32_bf16 v[92:95], v[24:27], v[64:67], 0
	v_mfma_f32_16x16x32_bf16 v[80:83], v[4:7], v[68:71], v[80:83]
	v_mfma_f32_16x16x32_bf16 v[84:87], v[12:15], v[68:71], v[84:87]
	v_mfma_f32_16x16x32_bf16 v[88:91], v[20:23], v[68:71], v[88:91]
	v_mfma_f32_16x16x32_bf16 v[92:95], v[28:31], v[68:71], v[92:95]
	global_load_dwordx4 v[64:67], v[152:153], off sc1
	global_load_dwordx4 v[68:71], v[152:153], off offset:1024 sc1
	v_max_f32_e32 v96, 0, v96
	v_max_f32_e32 v100, 0, v100
	v_max_f32_e32 v104, 0, v104
	v_max_f32_e32 v108, 0, v108
	v_max_f32_e32 v97, 0, v97
	v_max_f32_e32 v101, 0, v101
	v_max_f32_e32 v105, 0, v105
	v_max_f32_e32 v109, 0, v109
	v_max_f32_e32 v98, 0, v98
	v_max_f32_e32 v102, 0, v102
	v_max_f32_e32 v106, 0, v106
	v_max_f32_e32 v110, 0, v110
	v_max_f32_e32 v99, 0, v99
	v_max_f32_e32 v103, 0, v103
	v_max_f32_e32 v107, 0, v107
	v_max_f32_e32 v111, 0, v111
	v_mul_f32_e32 v133, v44, v96
	v_mul_f32_e32 v137, v40, v100
	v_mul_f32_e32 v141, v36, v104
	v_mul_f32_e32 v145, v32, v108
	v_fmac_f32_e32 v133, v45, v97
	v_fmac_f32_e32 v137, v41, v101
	v_fmac_f32_e32 v141, v37, v105
	v_fmac_f32_e32 v145, v33, v109
	v_fmac_f32_e32 v133, v46, v98
	v_fmac_f32_e32 v137, v42, v102
	v_fmac_f32_e32 v141, v38, v106
	v_fmac_f32_e32 v145, v34, v110
	v_fmac_f32_e32 v133, v47, v99
	v_fmac_f32_e32 v137, v43, v103
	v_fmac_f32_e32 v141, v39, v107
	v_fmac_f32_e32 v145, v35, v111
	s_waitcnt vmcnt(6)
	v_mfma_f32_16x16x32_bf16 v[96:99], v[0:3], v[72:75], 0
	v_mfma_f32_16x16x32_bf16 v[100:103], v[8:11], v[72:75], 0
	v_mfma_f32_16x16x32_bf16 v[104:107], v[16:19], v[72:75], 0
	v_mfma_f32_16x16x32_bf16 v[108:111], v[24:27], v[72:75], 0
	v_mfma_f32_16x16x32_bf16 v[96:99], v[4:7], v[76:79], v[96:99]
	v_mfma_f32_16x16x32_bf16 v[100:103], v[12:15], v[76:79], v[100:103]
	v_mfma_f32_16x16x32_bf16 v[104:107], v[20:23], v[76:79], v[104:107]
	v_mfma_f32_16x16x32_bf16 v[108:111], v[28:31], v[76:79], v[108:111]
	global_load_dwordx4 v[72:75], v[152:153], off offset:2048 sc1
	global_load_dwordx4 v[76:79], v[152:153], off offset:3072 sc1
	v_lshl_add_u64 v[150:151], v[150:151], 0, s[18:19]
	v_lshl_add_u64 v[152:153], v[152:153], 0, s[18:19]
	v_max_f32_e32 v80, 0, v80
	v_max_f32_e32 v84, 0, v84
	v_max_f32_e32 v88, 0, v88
	v_max_f32_e32 v92, 0, v92
	v_max_f32_e32 v81, 0, v81
	v_max_f32_e32 v85, 0, v85
	v_max_f32_e32 v89, 0, v89
	v_max_f32_e32 v93, 0, v93
	v_max_f32_e32 v82, 0, v82
	v_max_f32_e32 v86, 0, v86
	v_max_f32_e32 v90, 0, v90
	v_max_f32_e32 v94, 0, v94
	v_max_f32_e32 v83, 0, v83
	v_max_f32_e32 v87, 0, v87
	v_max_f32_e32 v91, 0, v91
	v_max_f32_e32 v95, 0, v95
	v_mul_f32_e32 v134, v44, v80
	v_mul_f32_e32 v138, v40, v84
	v_mul_f32_e32 v142, v36, v88
	v_mul_f32_e32 v146, v32, v92
	v_fmac_f32_e32 v134, v45, v81
	v_fmac_f32_e32 v138, v41, v85
	v_fmac_f32_e32 v142, v37, v89
	v_fmac_f32_e32 v146, v33, v93
	v_fmac_f32_e32 v134, v46, v82
	v_fmac_f32_e32 v138, v42, v86
	v_fmac_f32_e32 v142, v38, v90
	v_fmac_f32_e32 v146, v34, v94
	v_fmac_f32_e32 v134, v47, v83
	v_fmac_f32_e32 v138, v43, v87
	v_fmac_f32_e32 v142, v39, v91
	v_fmac_f32_e32 v146, v35, v95
	v_max_f32_e32 v96, 0, v96
	v_max_f32_e32 v100, 0, v100
	v_max_f32_e32 v104, 0, v104
	v_max_f32_e32 v108, 0, v108
	v_max_f32_e32 v97, 0, v97
	v_max_f32_e32 v101, 0, v101
	v_max_f32_e32 v105, 0, v105
	v_max_f32_e32 v109, 0, v109
	v_max_f32_e32 v98, 0, v98
	v_max_f32_e32 v102, 0, v102
	v_max_f32_e32 v106, 0, v106
	v_max_f32_e32 v110, 0, v110
	v_max_f32_e32 v99, 0, v99
	v_max_f32_e32 v103, 0, v103
	v_max_f32_e32 v107, 0, v107
	v_max_f32_e32 v111, 0, v111
	v_mul_f32_e32 v135, v44, v96
	v_mul_f32_e32 v139, v40, v100
	v_mul_f32_e32 v143, v36, v104
	v_mul_f32_e32 v147, v32, v108
	v_fmac_f32_e32 v135, v45, v97
	v_fmac_f32_e32 v139, v41, v101
	v_fmac_f32_e32 v143, v37, v105
	v_fmac_f32_e32 v147, v33, v109
	v_fmac_f32_e32 v135, v46, v98
	v_fmac_f32_e32 v139, v42, v102
	v_fmac_f32_e32 v143, v38, v106
	v_fmac_f32_e32 v147, v34, v110
	v_fmac_f32_e32 v135, v47, v99
	v_fmac_f32_e32 v139, v43, v103
	v_fmac_f32_e32 v143, v39, v107
	v_fmac_f32_e32 v147, v35, v111
	s_nop 1
	v_permlane32_swap_b32_e32 v132, v134
	v_permlane32_swap_b32_e32 v133, v135
	v_permlane32_swap_b32_e32 v136, v138
	v_permlane32_swap_b32_e32 v137, v139
	v_permlane32_swap_b32_e32 v140, v142
	v_permlane32_swap_b32_e32 v141, v143
	v_permlane32_swap_b32_e32 v144, v146
	v_permlane32_swap_b32_e32 v145, v147
	v_add_f32_e32 v112, v132, v134
	v_add_f32_e32 v113, v133, v135
	v_add_f32_e32 v114, v136, v138
	v_add_f32_e32 v115, v137, v139
	v_add_f32_e32 v116, v140, v142
	v_add_f32_e32 v117, v141, v143
	v_add_f32_e32 v118, v144, v146
	v_add_f32_e32 v119, v145, v147
	s_nop 1
	v_permlane16_swap_b32_e32 v112, v113
	v_permlane16_swap_b32_e32 v114, v115
	v_permlane16_swap_b32_e32 v116, v117
	v_permlane16_swap_b32_e32 v118, v119
	v_add_u32_e32 v156, 0x800, v130
	v_add_u32_e32 v157, 0x800, v155
	v_add_f32_e32 v120, v112, v113
	v_add_f32_e32 v121, v114, v115
	v_add_f32_e32 v122, v116, v117
	v_add_f32_e32 v123, v118, v119
	v_ashrrev_i32_e32 v112, 31, v120
	v_ashrrev_i32_e32 v113, 31, v121
	v_ashrrev_i32_e32 v114, 31, v122
	v_ashrrev_i32_e32 v115, 31, v123
	v_cmp_le_u32_e32 vcc, v154, v124
	v_cmp_le_u32_e64 s[16:17], v154, v128
	v_cmp_le_u32_e64 s[44:45], v154, v129
	v_cmp_le_u32_e64 s[78:79], v154, v126
	v_or_b32_e32 v112, 0x80000000, v112
	v_or_b32_e32 v113, 0x80000000, v113
	v_or_b32_e32 v114, 0x80000000, v114
	v_or_b32_e32 v115, 0x80000000, v115
	v_xor_b32_e32 v120, v120, v112
	v_xor_b32_e32 v121, v121, v113
	v_xor_b32_e32 v122, v122, v114
	v_xor_b32_e32 v123, v123, v115
	v_cndmask_b32_e32 v120, 0, v120, vcc
	v_cndmask_b32_e64 v121, 0, v121, s[16:17]
	v_cndmask_b32_e64 v122, 0, v122, s[44:45]
	v_cndmask_b32_e64 v123, 0, v123, s[78:79]
	ds_write2st64_b32 v130, v120, v121 offset1:128
	ds_write2st64_b32 v155, v122, v123 offset1:128
	v_mov_b32_e32 v130, v156
	v_mov_b32_e32 v155, v157
	v_add_u32_e32 v154, 0x200, v154
	s_add_i32 s20, s20, 1
	s_cmp_lt_u32 s20, s14
	s_cbranch_scc1 .Lidx_loop
	s_waitcnt vmcnt(0)
	s_branch .LBB0_479
	s_nop 0
	s_nop 0
	s_nop 0
	s_nop 0
	s_nop 0
	s_nop 0
	s_nop 0

; #define STG_LOAD(CK) do { _Pragma("unroll") for (int it = 0; it < 16; ++it) { const int pp = it * 64 + lane, kk = pp >> 5, cp = pp & 31; \
;         const int idx = (int)sel[q * 256 + slot0 + 32 * (CK) + kk]; stv[it] = *(const u32x4*)(P.CKV + (rowb + idx) * 256 + 8 * cp); } } while (0)
; __device__ __forceinline__ void attn_item(const Ptrs& P, unsigned char* lds, int b, int tq0, int tid) {
;     ...
;     const unsigned aseq = (xa[40 + w] + 1u) & 0xffffu; if (lane == 0) xa[40 + w] = aseq;
;     float mrun[4], lrun[4];
; #pragma unroll
;     for (int j = 0; j < 4; ++j) { mrun[j] = -1e30f; lrun[j] = 0.f; }
;     f32x4 oacc[16];
; #pragma unroll
;     for (int dt = 0; dt < 16; ++dt) oacc[dt] = (f32x4){0.f, 0.f, 0.f, 0.f};
;     const int qq = r16 >> 2, pp4 = lane & 3;
;     const unsigned tr_base = (unsigned)(uintptr_t)stw + (unsigned)(((8 * g + qq) * SP + 4 * pp4) * 2);
;     const int slot0 = 128 * half;
;     ...
;     u32x4 stv[16];
;     STG_LOAD(0);
.LBB0_923:
	s_or_b64 exec, exec, s[12:13]
	v_lshlrev_b32_e32 v33, 8, v219
	s_add_i32 s14, 0, 0x21000
	v_lshl_add_u32 v36, v32, 9, v33
	v_add_u32_e32 v37, s14, v36
	v_lshl_add_u32 v32, v197, 1, v37
	ds_read_u16 v33, v32
	ds_read_u16 v34, v32 offset:4
	ds_read_u16 v38, v32 offset:8
	ds_read_u16 v39, v32 offset:12
	ds_read_u16 v40, v32 offset:16
	ds_read_u16 v41, v32 offset:20
	ds_read_u16 v42, v32 offset:24
	ds_read_u16 v43, v32 offset:28
	ds_read_u16 v44, v32 offset:32
	ds_read_u16 v45, v32 offset:36
	ds_read_u16 v46, v32 offset:40
	ds_read_u16 v47, v32 offset:44
	ds_read_u16 v48, v32 offset:48
	ds_read_u16 v49, v32 offset:52
	ds_read_u16 v50, v32 offset:56
	s_waitcnt lgkmcnt(0)
	v_add_lshl_u32 v32, s82, v34, 9
	v_add_lshl_u32 v34, s81, v33, 9
	v_mov_b32_e32 v35, v165
	v_mov_b32_e32 v33, v165
	v_lshl_add_u64 v[34:35], v[174:175], 0, v[34:35]
	v_lshl_add_u64 v[32:33], v[174:175], 0, v[32:33]
	global_load_dwordx4 v[52:55], v[34:35], off sc1
	global_load_dwordx4 v[56:59], v[32:33], off sc1
	v_add_lshl_u32 v32, s82, v39, 9
	v_add_lshl_u32 v34, s81, v38, 9
	v_mov_b32_e32 v35, v165
	v_mov_b32_e32 v33, v165
	v_lshl_add_u64 v[34:35], v[174:175], 0, v[34:35]
	v_lshl_add_u64 v[32:33], v[174:175], 0, v[32:33]
	global_load_dwordx4 v[60:63], v[34:35], off sc1
	global_load_dwordx4 v[64:67], v[32:33], off sc1
	v_add_lshl_u32 v32, s82, v41, 9
	v_add_lshl_u32 v34, s81, v40, 9
	v_mov_b32_e32 v35, v165
	v_mov_b32_e32 v33, v165
	v_lshl_add_u64 v[34:35], v[174:175], 0, v[34:35]
	v_lshl_add_u64 v[32:33], v[174:175], 0, v[32:33]
	global_load_dwordx4 v[72:75], v[34:35], off sc1
	global_load_dwordx4 v[76:79], v[32:33], off sc1
	v_add_lshl_u32 v32, s82, v43, 9
	v_add_lshl_u32 v34, s81, v42, 9
	v_mov_b32_e32 v35, v165
	v_mov_b32_e32 v33, v165
	v_lshl_add_u64 v[34:35], v[174:175], 0, v[34:35]
	v_lshl_add_u64 v[32:33], v[174:175], 0, v[32:33]
	global_load_dwordx4 v[88:91], v[34:35], off sc1
	global_load_dwordx4 v[92:95], v[32:33], off sc1
	v_add_lshl_u32 v32, s82, v45, 9
	v_add_lshl_u32 v34, s81, v44, 9
	v_mov_b32_e32 v35, v165
	v_mov_b32_e32 v33, v165
	v_lshl_add_u64 v[34:35], v[174:175], 0, v[34:35]
	v_lshl_add_u64 v[32:33], v[174:175], 0, v[32:33]
	global_load_dwordx4 v[116:119], v[34:35], off sc1
	global_load_dwordx4 v[120:123], v[32:33], off sc1
	v_add_lshl_u32 v32, s82, v47, 9
	v_add_lshl_u32 v34, s81, v46, 9
	v_mov_b32_e32 v35, v165
	v_mov_b32_e32 v33, v165
	v_lshl_add_u64 v[34:35], v[174:175], 0, v[34:35]
	v_lshl_add_u64 v[32:33], v[174:175], 0, v[32:33]
	global_load_dwordx4 v[128:131], v[34:35], off sc1
	global_load_dwordx4 v[132:135], v[32:33], off sc1
	v_lshl_add_u32 v33, v198, 1, v37
	ds_read_u16 v37, v33
	v_add_lshl_u32 v34, s81, v48, 9
	v_mov_b32_e32 v35, v165
	v_add_lshl_u32 v32, s82, v49, 9
	v_lshl_add_u64 v[34:35], v[174:175], 0, v[34:35]
	v_mov_b32_e32 v33, v165
	v_lshl_add_u64 v[32:33], v[174:175], 0, v[32:33]
	global_load_dwordx4 v[140:143], v[34:35], off sc1
	global_load_dwordx4 v[144:147], v[32:33], off sc1
	v_add_lshl_u32 v34, s81, v50, 9
	v_mov_b32_e32 v35, v165
	s_waitcnt lgkmcnt(0)
	v_add_lshl_u32 v32, s82, v37, 9
	v_lshl_add_u64 v[34:35], v[174:175], 0, v[34:35]
	v_mov_b32_e32 v33, v165
	v_lshl_add_u64 v[32:33], v[174:175], 0, v[32:33]
	global_load_dwordx4 v[152:155], v[34:35], off sc1
	global_load_dwordx4 v[156:159], v[32:33], off sc1
	s_mul_i32 s13, s62, 0x500
	s_mul_i32 s12, s62, 0x4200
	s_add_i32 s13, s13, 0
	s_add_i32 s12, s12, 0
	s_add_i32 s13, s13, 0x21800
	v_lshlrev_b32_e32 v181, 7, v219
	v_lshl_add_u32 v32, v196, 1, s12
	v_add_u32_e32 v33, s13, v164
	v_add_u32_e32 v34, s12, v164
	v_lshlrev_b32_e32 v35, 1, v194
	v_mov_b32_e32 v44, 0
	s_add_i32 s16, s16, 0x24000
	v_min_u32_e32 v221, 0xff, v220
	v_add_u32_e32 v222, s12, v205
	v_add3_u32 v223, s13, v35, v214
	v_add3_u32 v224, s13, v214, v35
	v_add_u32_e32 v225, v211, v36
	v_add_u32_e32 v226, v212, v36
	v_or_b32_e32 v227, v194, v181
	v_add_u32_e32 v228, v213, v36
	v_mov_b32_e32 v162, 0xf149f2ca
	s_movk_i32 s13, 0xff00
	v_add_u32_e32 v229, v32, v200
	v_add_u32_e32 v230, v32, v201
	v_add_u32_e32 v231, v34, v202
	v_add_u32_e32 v232, v33, v199
	v_mov_b32_e32 v163, 0xf149f2ca
	v_mov_b32_e32 v160, 0xf149f2ca
	v_mov_b32_e32 v161, 0xf149f2ca
	v_mov_b32_e32 v45, v44
	v_mov_b32_e32 v46, v44
	v_mov_b32_e32 v47, v44
	v_mov_b32_e32 v80, v44
	v_mov_b32_e32 v81, v44
	v_mov_b32_e32 v82, v44
	v_mov_b32_e32 v83, v44
	v_mov_b32_e32 v96, v44
	v_mov_b32_e32 v97, v44
	v_mov_b32_e32 v98, v44
	v_mov_b32_e32 v99, v44
	v_mov_b32_e32 v104, v44
	v_mov_b32_e32 v105, v44
	v_mov_b32_e32 v106, v44
	v_mov_b32_e32 v107, v44
	v_mov_b32_e32 v112, v44
	v_mov_b32_e32 v113, v44
	v_mov_b32_e32 v114, v44
	v_mov_b32_e32 v115, v44
	v_mov_b32_e32 v124, v44
	v_mov_b32_e32 v125, v44
	v_mov_b32_e32 v126, v44
	v_mov_b32_e32 v127, v44
	v_mov_b32_e32 v136, v44
	v_mov_b32_e32 v137, v44
	v_mov_b32_e32 v138, v44
	v_mov_b32_e32 v139, v44
	v_mov_b32_e32 v148, v44
	v_mov_b32_e32 v149, v44
	v_mov_b32_e32 v150, v44
	v_mov_b32_e32 v151, v44
	v_mov_b32_e32 v32, v44
	v_mov_b32_e32 v33, v44
	v_mov_b32_e32 v34, v44
	v_mov_b32_e32 v35, v44
	v_mov_b32_e32 v36, v44
	v_mov_b32_e32 v37, v44
	v_mov_b32_e32 v38, v44
	v_mov_b32_e32 v39, v44
	v_mov_b32_e32 v40, v44
	v_mov_b32_e32 v41, v44
	v_mov_b32_e32 v42, v44
	v_mov_b32_e32 v43, v44
	v_mov_b32_e32 v48, v44
	v_mov_b32_e32 v49, v44
	v_mov_b32_e32 v50, v44
	v_mov_b32_e32 v51, v44
	v_mov_b32_e32 v68, v44
	v_mov_b32_e32 v69, v44
	v_mov_b32_e32 v70, v44
	v_mov_b32_e32 v71, v44
	v_mov_b32_e32 v84, v44
	v_mov_b32_e32 v85, v44
	v_mov_b32_e32 v86, v44
	v_mov_b32_e32 v87, v44
	v_mov_b32_e32 v100, v44
	v_mov_b32_e32 v101, v44
	v_mov_b32_e32 v102, v44
	v_mov_b32_e32 v103, v44
	v_mov_b32_e32 v108, v44
	v_mov_b32_e32 v109, v44
	v_mov_b32_e32 v110, v44
	v_mov_b32_e32 v111, v44
	v_mov_b32_e32 v186, v44
	v_mov_b32_e32 v187, v44
	v_mov_b32_e32 v190, v44
	v_mov_b32_e32 v191, v44
; #define STG_LOAD(CK) do { _Pragma("unroll") for (int it = 0; it < 16; ++it) { const int pp = it * 64 + lane, kk = pp >> 5, cp = pp & 31; \
;         const int idx = (int)sel[q * 256 + slot0 + 32 * (CK) + kk]; stv[it] = *(const u32x4*)(P.CKV + (rowb + idx) * 256 + 8 * cp); } } while (0)
; __device__ __forceinline__ void attn_item(const Ptrs& P, unsigned char* lds, int b, int tq0, int tid) {
;     ...
;     for (int ck = 0; ck < 4; ++ck) {
; #pragma unroll
;         for (int it = 0; it < 16; ++it) { const int pp = it * 64 + lane, kk = pp >> 5, cp = pp & 31; *(u32x4*)(stw + kk * SP + 8 * cp) = stv[it]; }
;         if (ck < 3) STG_LOAD(ck + 1);
.LBB0_924:
	s_cmpk_lg_i32 s13, 0xffc0
	s_waitcnt vmcnt(15)
	ds_write_b128 v229, v[52:55]
	s_waitcnt vmcnt(14)
	ds_write_b128 v229, v[56:59] offset:1056
	s_waitcnt vmcnt(13)
	ds_write_b128 v229, v[60:63] offset:2112
	s_waitcnt vmcnt(12)
	ds_write_b128 v229, v[64:67] offset:3168
	s_waitcnt vmcnt(11)
	ds_write_b128 v229, v[72:75] offset:4224
	s_waitcnt vmcnt(10)
	ds_write_b128 v229, v[76:79] offset:5280
	s_waitcnt vmcnt(9)
	ds_write_b128 v229, v[88:91] offset:6336
	s_waitcnt vmcnt(8)
	ds_write_b128 v229, v[92:95] offset:7392
	s_waitcnt vmcnt(7)
	ds_write_b128 v229, v[116:119] offset:8448
	s_waitcnt vmcnt(6)
	ds_write_b128 v229, v[120:123] offset:9504
	s_waitcnt vmcnt(5)
	ds_write_b128 v229, v[128:131] offset:10560
	s_waitcnt vmcnt(4)
	ds_write_b128 v229, v[132:135] offset:11616
	s_waitcnt vmcnt(3)
	ds_write_b128 v229, v[140:143] offset:12672
	s_waitcnt vmcnt(2)
	ds_write_b128 v229, v[144:147] offset:13728
	s_waitcnt vmcnt(1)
	ds_write_b128 v229, v[152:155] offset:14784
	s_waitcnt vmcnt(0)
	ds_write_b128 v230, v[156:159]
	s_cbranch_scc0 .LBB0_926
	v_add_u32_e32 v116, s13, v228
	v_add_u32_e32 v52, 0x21140, v116
	v_add_u32_e32 v53, 0x21144, v116
	v_add_u32_e32 v54, 0x21148, v116
	v_add_u32_e32 v55, 0x2114c, v116
	v_add_u32_e32 v56, 0x21150, v116
	v_add_u32_e32 v57, 0x21154, v116
	v_add_u32_e32 v58, 0x21158, v116
	v_add_u32_e32 v59, 0x2115c, v116
	ds_read_u16 v60, v52
	ds_read_u16 v52, v53
	ds_read_u16 v61, v54
	ds_read_u16 v62, v55
	ds_read_u16 v73, v56
	ds_read_u16 v72, v57
	ds_read_u16 v89, v58
	ds_read_u16 v88, v59
	s_waitcnt lgkmcnt(7)
	v_add_lshl_u32 v164, s81, v60, 9
	v_lshl_add_u64 v[54:55], v[174:175], 0, v[164:165]
	s_waitcnt lgkmcnt(5)
	v_add_lshl_u32 v164, s81, v61, 9
	s_waitcnt lgkmcnt(4)
	v_add_lshl_u32 v60, s82, v62, 9
	v_lshl_add_u64 v[62:63], v[174:175], 0, v[164:165]
	s_waitcnt lgkmcnt(3)
	v_add_lshl_u32 v164, s81, v73, 9
	v_add_lshl_u32 v52, s82, v52, 9
	v_mov_b32_e32 v53, v165
	v_mov_b32_e32 v61, v165
	s_waitcnt lgkmcnt(2)
	v_add_lshl_u32 v72, s82, v72, 9
	v_lshl_add_u64 v[74:75], v[174:175], 0, v[164:165]
	v_mov_b32_e32 v73, v165
	s_waitcnt lgkmcnt(0)
	v_add_lshl_u32 v88, s82, v88, 9
	v_add_lshl_u32 v164, s81, v89, 9
	v_mov_b32_e32 v89, v165
	v_lshl_add_u64 v[56:57], v[174:175], 0, v[52:53]
	v_lshl_add_u64 v[64:65], v[174:175], 0, v[60:61]
	v_lshl_add_u64 v[76:77], v[174:175], 0, v[72:73]
	v_lshl_add_u64 v[90:91], v[174:175], 0, v[164:165]
	v_lshl_add_u64 v[92:93], v[174:175], 0, v[88:89]
	v_add_u32_e32 v117, 0x21160, v116
	v_add_u32_e32 v118, 0x21164, v116
	global_load_dwordx4 v[52:55], v[54:55], off sc1
	s_nop 0
	global_load_dwordx4 v[56:59], v[56:57], off sc1
	s_nop 0
	global_load_dwordx4 v[60:63], v[62:63], off sc1
	s_nop 0
	global_load_dwordx4 v[64:67], v[64:65], off sc1
	s_nop 0
	global_load_dwordx4 v[72:75], v[74:75], off sc1
	s_nop 0
	global_load_dwordx4 v[76:79], v[76:77], off sc1
	s_nop 0
	global_load_dwordx4 v[88:91], v[90:91], off sc1
	s_nop 0
	global_load_dwordx4 v[92:95], v[92:93], off sc1
	v_add_u32_e32 v119, 0x21168, v116
	v_add_u32_e32 v120, 0x2116c, v116
	v_add_u32_e32 v121, 0x21170, v116
	v_add_u32_e32 v122, 0x21174, v116
	v_add_u32_e32 v116, 0x21178, v116
	v_add_u32_e32 v123, s13, v225
	ds_read_u16 v117, v117
	ds_read_u16 v118, v118
	ds_read_u16 v129, v119
	ds_read_u16 v128, v120
	ds_read_u16 v141, v121
	ds_read_u16 v140, v122
	ds_read_u16 v153, v116
	ds_read_u16 v152, v123 offset:256
	s_waitcnt lgkmcnt(7)
	v_add_lshl_u32 v164, s81, v117, 9
	s_waitcnt lgkmcnt(6)
	v_add_lshl_u32 v116, s82, v118, 9
	v_lshl_add_u64 v[118:119], v[174:175], 0, v[164:165]
	s_waitcnt lgkmcnt(5)
	v_add_lshl_u32 v164, s81, v129, 9
	v_lshl_add_u64 v[130:131], v[174:175], 0, v[164:165]
	s_waitcnt lgkmcnt(3)
	v_add_lshl_u32 v164, s81, v141, 9
	v_mov_b32_e32 v117, v165
	v_add_lshl_u32 v128, s82, v128, 9
	v_mov_b32_e32 v129, v165
	s_waitcnt lgkmcnt(2)
	v_add_lshl_u32 v140, s82, v140, 9
	v_lshl_add_u64 v[142:143], v[174:175], 0, v[164:165]
	v_mov_b32_e32 v141, v165
	s_waitcnt lgkmcnt(0)
	v_add_lshl_u32 v152, s82, v152, 9
	v_add_lshl_u32 v164, s81, v153, 9
	v_mov_b32_e32 v153, v165
	v_lshl_add_u64 v[120:121], v[174:175], 0, v[116:117]
	v_lshl_add_u64 v[132:133], v[174:175], 0, v[128:129]
	v_lshl_add_u64 v[144:145], v[174:175], 0, v[140:141]
	v_lshl_add_u64 v[154:155], v[174:175], 0, v[164:165]
	v_lshl_add_u64 v[156:157], v[174:175], 0, v[152:153]
	global_load_dwordx4 v[116:119], v[118:119], off sc1
	s_nop 0
	global_load_dwordx4 v[120:123], v[120:121], off sc1
	s_nop 0
	global_load_dwordx4 v[128:131], v[130:131], off sc1
	s_nop 0
	global_load_dwordx4 v[132:135], v[132:133], off sc1
	s_nop 0
	global_load_dwordx4 v[140:143], v[142:143], off sc1
	s_nop 0
	global_load_dwordx4 v[144:147], v[144:145], off sc1
	s_nop 0
	global_load_dwordx4 v[152:155], v[154:155], off sc1
	s_nop 0
	global_load_dwordx4 v[156:159], v[156:157], off sc1
